# top-k bisection: compares issued in groups of 3 into separate SGPR pairs ahead of their dependent v_addc (breaks back-to-back VALU->SGPR->VALU carry dependency)
# baseline (speedup 1.0000x reference)
;     ...
;         const unsigned cand = T | (1u << bit);
;         unsigned c0 = 0u;
; #pragma unroll
;         for (int j = 0; j < NJ; ++j) asm("v_cmp_ge_u32_e32 vcc, %1, %2\n\tv_addc_co_u32_e32 %0, vcc, 0, %0, vcc" : "+v"(c0) : "v"(key[j]), "v"(cand) : "vcc");
;         const int cnt = wave_count6(c0);
;         if (cnt >= 256) T = cand;
;         if (cnt == 256) break;
;     }
;     unsigned cg = 0u, ce = 0u;
; #pragma unroll
;     for (int j = 0; j < NJ; ++j) { asm("v_cmp_gt_u32_e32 vcc, %1, %2\n\tv_addc_co_u32_e32 %0, vcc, 0, %0, vcc" : "+v"(cg) : "v"(key[j]), "v"(T) : "vcc");
;                                    asm("v_cmp_eq_u32_e32 vcc, %1, %2\n\tv_addc_co_u32_e32 %0, vcc, 0, %0, vcc" : "+v"(ce) : "v"(key[j]), "v"(T) : "vcc"); }
;     const int gt = wave_count6(cg), eq = wave_count6(ce);
;     const int need = 256 - gt; int lim = SEQ;
.LBB0_449:
	v_lshlrev_b32_e64 v58, v57, 1
	v_mov_b32_e32 v59, 0
	v_or_b32_e32 v58, v58, v56
	v_cmp_ge_u32_e32 vcc, v1, v58
	v_cmp_ge_u32_e64 s[100:101], v0, v58
	v_cmp_ge_u32_e64 s[0:1], v3, v58
	v_addc_co_u32_e32 v59, vcc, 0, v59, vcc
	v_addc_co_u32_e64 v59, s[100:101], 0, v59, s[100:101]
	v_addc_co_u32_e64 v59, s[0:1], 0, v59, s[0:1]
	v_cmp_ge_u32_e32 vcc, v2, v58
	v_cmp_ge_u32_e64 s[100:101], v5, v58
	v_cmp_ge_u32_e64 s[0:1], v4, v58
	v_addc_co_u32_e32 v59, vcc, 0, v59, vcc
	v_addc_co_u32_e64 v59, s[100:101], 0, v59, s[100:101]
	v_addc_co_u32_e64 v59, s[0:1], 0, v59, s[0:1]
	v_cmp_ge_u32_e32 vcc, v7, v58
	v_cmp_ge_u32_e64 s[100:101], v6, v58
	v_cmp_ge_u32_e64 s[0:1], v9, v58
	v_addc_co_u32_e32 v59, vcc, 0, v59, vcc
	v_addc_co_u32_e64 v59, s[100:101], 0, v59, s[100:101]
	v_addc_co_u32_e64 v59, s[0:1], 0, v59, s[0:1]
	v_cmp_ge_u32_e32 vcc, v8, v58
	v_cmp_ge_u32_e64 s[100:101], v11, v58
	v_cmp_ge_u32_e64 s[0:1], v10, v58
	v_addc_co_u32_e32 v59, vcc, 0, v59, vcc
	v_addc_co_u32_e64 v59, s[100:101], 0, v59, s[100:101]
	v_addc_co_u32_e64 v59, s[0:1], 0, v59, s[0:1]
	v_cmp_ge_u32_e32 vcc, v13, v58
	v_cmp_ge_u32_e64 s[100:101], v12, v58
	v_cmp_ge_u32_e64 s[0:1], v15, v58
	v_addc_co_u32_e32 v59, vcc, 0, v59, vcc
	v_addc_co_u32_e64 v59, s[100:101], 0, v59, s[100:101]
	v_addc_co_u32_e64 v59, s[0:1], 0, v59, s[0:1]
	v_cmp_ge_u32_e32 vcc, v14, v58
	v_cmp_ge_u32_e64 s[100:101], v17, v58
	v_cmp_ge_u32_e64 s[0:1], v16, v58
	v_addc_co_u32_e32 v59, vcc, 0, v59, vcc
	v_addc_co_u32_e64 v59, s[100:101], 0, v59, s[100:101]
	v_addc_co_u32_e64 v59, s[0:1], 0, v59, s[0:1]
	v_cmp_ge_u32_e32 vcc, v19, v58
	v_cmp_ge_u32_e64 s[100:101], v18, v58
	v_cmp_ge_u32_e64 s[0:1], v21, v58
	v_addc_co_u32_e32 v59, vcc, 0, v59, vcc
	v_addc_co_u32_e64 v59, s[100:101], 0, v59, s[100:101]
	v_addc_co_u32_e64 v59, s[0:1], 0, v59, s[0:1]
	v_cmp_ge_u32_e32 vcc, v20, v58
	v_cmp_ge_u32_e64 s[100:101], v23, v58
	v_cmp_ge_u32_e64 s[0:1], v22, v58
	v_addc_co_u32_e32 v59, vcc, 0, v59, vcc
	v_addc_co_u32_e64 v59, s[100:101], 0, v59, s[100:101]
	v_addc_co_u32_e64 v59, s[0:1], 0, v59, s[0:1]
	v_cmp_ge_u32_e32 vcc, v25, v58
	v_cmp_ge_u32_e64 s[100:101], v24, v58
	v_cmp_ge_u32_e64 s[0:1], v27, v58
	v_addc_co_u32_e32 v59, vcc, 0, v59, vcc
	v_addc_co_u32_e64 v59, s[100:101], 0, v59, s[100:101]
	v_addc_co_u32_e64 v59, s[0:1], 0, v59, s[0:1]
	v_cmp_ge_u32_e32 vcc, v26, v58
	v_cmp_ge_u32_e64 s[100:101], v29, v58
	v_cmp_ge_u32_e64 s[0:1], v28, v58
	v_addc_co_u32_e32 v59, vcc, 0, v59, vcc
	v_addc_co_u32_e64 v59, s[100:101], 0, v59, s[100:101]
	v_addc_co_u32_e64 v59, s[0:1], 0, v59, s[0:1]
	v_cmp_ge_u32_e32 vcc, v31, v58
	v_cmp_ge_u32_e64 s[100:101], v30, v58
	v_addc_co_u32_e32 v59, vcc, 0, v59, vcc
	v_addc_co_u32_e64 v59, s[100:101], 0, v59, s[100:101]
	s_nop 1
	v_add_u32_dpp v59, v59, v59 row_shr:1 row_mask:0xf bank_mask:0xf bound_ctrl:1
	s_nop 1
	v_add_u32_dpp v59, v59, v59 row_shr:2 row_mask:0xf bank_mask:0xf bound_ctrl:1
	s_nop 1
	v_add_u32_dpp v59, v59, v59 row_shr:4 row_mask:0xf bank_mask:0xf bound_ctrl:1
	s_nop 1
	v_add_u32_dpp v59, v59, v59 row_shr:8 row_mask:0xf bank_mask:0xf bound_ctrl:1
	s_nop 1
	v_add_u32_dpp v59, v59, v59 row_bcast:15 row_mask:0xa bank_mask:0xf
	s_nop 1
	v_add_u32_dpp v59, v59, v59 row_bcast:31 row_mask:0xc bank_mask:0xf
	s_nop 0
	v_readlane_b32 s0, v59, 63
	s_cmpk_gt_i32 s0, 0xff
	s_cselect_b64 vcc, -1, 0
	s_cmpk_eq_i32 s0, 0x100
	v_cndmask_b32_e32 v56, v56, v58, vcc
	s_cselect_b64 s[0:1], -1, 0
	v_subrev_co_u32_e32 v57, vcc, 1, v57
	s_or_b64 s[0:1], s[0:1], vcc
	s_andn2_b64 vcc, exec, s[0:1]
	s_cbranch_vccnz .LBB0_449
	v_mov_b32_e32 v57, v98
	v_cmp_gt_u32_e32 vcc, v1, v56
	v_addc_co_u32_e32 v57, vcc, 0, v57, vcc
	v_mov_b32_e32 v58, v98
	v_cmp_gt_u32_e32 vcc, v0, v56
	v_addc_co_u32_e32 v57, vcc, 0, v57, vcc
	s_movk_i32 s64, 0x800
	v_cmp_gt_u32_e32 vcc, v3, v56
	v_addc_co_u32_e32 v57, vcc, 0, v57, vcc
	v_cmp_gt_u32_e32 vcc, v2, v56
	v_addc_co_u32_e32 v57, vcc, 0, v57, vcc
	v_cmp_gt_u32_e32 vcc, v5, v56
	v_addc_co_u32_e32 v57, vcc, 0, v57, vcc
	v_cmp_gt_u32_e32 vcc, v4, v56
	v_addc_co_u32_e32 v57, vcc, 0, v57, vcc
	v_cmp_gt_u32_e32 vcc, v7, v56
	v_addc_co_u32_e32 v57, vcc, 0, v57, vcc
	v_cmp_eq_u32_e32 vcc, v1, v56
	v_addc_co_u32_e32 v58, vcc, 0, v58, vcc
	v_cmp_gt_u32_e32 vcc, v6, v56
	v_addc_co_u32_e32 v57, vcc, 0, v57, vcc
	v_cmp_eq_u32_e32 vcc, v0, v56
	v_addc_co_u32_e32 v58, vcc, 0, v58, vcc
	v_cmp_gt_u32_e32 vcc, v9, v56
	v_addc_co_u32_e32 v57, vcc, 0, v57, vcc
	v_cmp_eq_u32_e32 vcc, v3, v56
	v_addc_co_u32_e32 v58, vcc, 0, v58, vcc
	v_cmp_gt_u32_e32 vcc, v8, v56
	v_addc_co_u32_e32 v57, vcc, 0, v57, vcc
	v_cmp_eq_u32_e32 vcc, v2, v56
	v_addc_co_u32_e32 v58, vcc, 0, v58, vcc
	v_cmp_gt_u32_e32 vcc, v11, v56
	v_addc_co_u32_e32 v57, vcc, 0, v57, vcc
	v_cmp_eq_u32_e32 vcc, v5, v56
	v_addc_co_u32_e32 v58, vcc, 0, v58, vcc
	v_cmp_gt_u32_e32 vcc, v10, v56
	v_addc_co_u32_e32 v57, vcc, 0, v57, vcc
	v_cmp_eq_u32_e32 vcc, v4, v56
	v_addc_co_u32_e32 v58, vcc, 0, v58, vcc
	v_cmp_gt_u32_e32 vcc, v13, v56
	v_addc_co_u32_e32 v57, vcc, 0, v57, vcc
	v_cmp_eq_u32_e32 vcc, v7, v56
	v_addc_co_u32_e32 v58, vcc, 0, v58, vcc
	v_cmp_gt_u32_e32 vcc, v12, v56
	v_addc_co_u32_e32 v57, vcc, 0, v57, vcc
	v_cmp_eq_u32_e32 vcc, v6, v56
	v_addc_co_u32_e32 v58, vcc, 0, v58, vcc
	v_cmp_gt_u32_e32 vcc, v15, v56
	v_addc_co_u32_e32 v57, vcc, 0, v57, vcc
	v_cmp_eq_u32_e32 vcc, v9, v56
;     ...
;     for (int j = 0; j < NJ; ++j) { asm("v_cmp_gt_u32_e32 vcc, %1, %2\n\tv_addc_co_u32_e32 %0, vcc, 0, %0, vcc" : "+v"(cg) : "v"(key[j]), "v"(T) : "vcc");
;                                    asm("v_cmp_eq_u32_e32 vcc, %1, %2\n\tv_addc_co_u32_e32 %0, vcc, 0, %0, vcc" : "+v"(ce) : "v"(key[j]), "v"(T) : "vcc"); }
;     const int gt = wave_count6(cg), eq = wave_count6(ce);
;     const int need = 256 - gt; int lim = SEQ;
;     if (eq > need) {
;         int X = 0;
; #pragma unroll 1
;     ...
; #pragma unroll
;             for (int j = 0; j < NJ; ++j) f += (key[j] == T && lane < c - 64 * j) ? 1u : 0u;
;             if (wave_count6(f) < need) X = c; }
;         lim = X + 1;
;     }
	v_addc_co_u32_e32 v58, vcc, 0, v58, vcc
	v_cmp_gt_u32_e32 vcc, v14, v56
	v_addc_co_u32_e32 v57, vcc, 0, v57, vcc
	v_cmp_eq_u32_e32 vcc, v8, v56
	v_addc_co_u32_e32 v58, vcc, 0, v58, vcc
	v_cmp_gt_u32_e32 vcc, v17, v56
	v_addc_co_u32_e32 v57, vcc, 0, v57, vcc
	v_cmp_eq_u32_e32 vcc, v11, v56
	v_addc_co_u32_e32 v58, vcc, 0, v58, vcc
	v_cmp_gt_u32_e32 vcc, v16, v56
	v_addc_co_u32_e32 v57, vcc, 0, v57, vcc
	v_cmp_eq_u32_e32 vcc, v10, v56
	v_addc_co_u32_e32 v58, vcc, 0, v58, vcc
	v_cmp_gt_u32_e32 vcc, v19, v56
	v_addc_co_u32_e32 v57, vcc, 0, v57, vcc
	v_cmp_eq_u32_e32 vcc, v13, v56
	v_addc_co_u32_e32 v58, vcc, 0, v58, vcc
	v_cmp_gt_u32_e32 vcc, v18, v56
	v_addc_co_u32_e32 v57, vcc, 0, v57, vcc
	v_cmp_eq_u32_e32 vcc, v12, v56
	v_addc_co_u32_e32 v58, vcc, 0, v58, vcc
	v_cmp_gt_u32_e32 vcc, v21, v56
	v_addc_co_u32_e32 v57, vcc, 0, v57, vcc
	v_cmp_eq_u32_e32 vcc, v15, v56
	v_addc_co_u32_e32 v58, vcc, 0, v58, vcc
	v_cmp_gt_u32_e32 vcc, v20, v56
	v_addc_co_u32_e32 v57, vcc, 0, v57, vcc
	v_cmp_eq_u32_e32 vcc, v14, v56
	v_addc_co_u32_e32 v58, vcc, 0, v58, vcc
	v_cmp_gt_u32_e32 vcc, v23, v56
	v_addc_co_u32_e32 v57, vcc, 0, v57, vcc
	v_cmp_eq_u32_e32 vcc, v17, v56
	v_addc_co_u32_e32 v58, vcc, 0, v58, vcc
	v_cmp_gt_u32_e32 vcc, v22, v56
	v_addc_co_u32_e32 v57, vcc, 0, v57, vcc
	v_cmp_eq_u32_e32 vcc, v16, v56
	v_addc_co_u32_e32 v58, vcc, 0, v58, vcc
	v_cmp_gt_u32_e32 vcc, v25, v56
	v_addc_co_u32_e32 v57, vcc, 0, v57, vcc
	v_cmp_eq_u32_e32 vcc, v19, v56
	v_addc_co_u32_e32 v58, vcc, 0, v58, vcc
	v_cmp_gt_u32_e32 vcc, v24, v56
	v_addc_co_u32_e32 v57, vcc, 0, v57, vcc
	v_cmp_eq_u32_e32 vcc, v18, v56
	v_addc_co_u32_e32 v58, vcc, 0, v58, vcc
	v_cmp_gt_u32_e32 vcc, v27, v56
	v_addc_co_u32_e32 v57, vcc, 0, v57, vcc
	v_cmp_eq_u32_e32 vcc, v21, v56
	v_addc_co_u32_e32 v58, vcc, 0, v58, vcc
	v_cmp_gt_u32_e32 vcc, v26, v56
	v_addc_co_u32_e32 v57, vcc, 0, v57, vcc
	v_cmp_eq_u32_e32 vcc, v20, v56
	v_addc_co_u32_e32 v58, vcc, 0, v58, vcc
	v_cmp_gt_u32_e32 vcc, v29, v56
	v_addc_co_u32_e32 v57, vcc, 0, v57, vcc
	v_cmp_eq_u32_e32 vcc, v23, v56
	v_addc_co_u32_e32 v58, vcc, 0, v58, vcc
	v_cmp_gt_u32_e32 vcc, v28, v56
	v_addc_co_u32_e32 v57, vcc, 0, v57, vcc
	v_cmp_eq_u32_e32 vcc, v22, v56
	v_addc_co_u32_e32 v58, vcc, 0, v58, vcc
	v_cmp_gt_u32_e32 vcc, v31, v56
	v_addc_co_u32_e32 v57, vcc, 0, v57, vcc
	v_cmp_eq_u32_e32 vcc, v25, v56
	v_addc_co_u32_e32 v58, vcc, 0, v58, vcc
	v_cmp_gt_u32_e32 vcc, v30, v56
	v_addc_co_u32_e32 v57, vcc, 0, v57, vcc
	v_cmp_eq_u32_e32 vcc, v24, v56
	v_addc_co_u32_e32 v58, vcc, 0, v58, vcc
	s_nop 0
	v_add_u32_dpp v57, v57, v57 row_shr:1 row_mask:0xf bank_mask:0xf bound_ctrl:1
	v_cmp_eq_u32_e32 vcc, v27, v56
	v_addc_co_u32_e32 v58, vcc, 0, v58, vcc
	v_cmp_eq_u32_e32 vcc, v26, v56
	v_addc_co_u32_e32 v58, vcc, 0, v58, vcc
	s_nop 0
	v_add_u32_dpp v57, v57, v57 row_shr:2 row_mask:0xf bank_mask:0xf bound_ctrl:1
	v_cmp_eq_u32_e32 vcc, v29, v56
	v_addc_co_u32_e32 v58, vcc, 0, v58, vcc
	v_cmp_eq_u32_e32 vcc, v28, v56
	v_addc_co_u32_e32 v58, vcc, 0, v58, vcc
	s_nop 0
	v_add_u32_dpp v57, v57, v57 row_shr:4 row_mask:0xf bank_mask:0xf bound_ctrl:1
	v_cmp_eq_u32_e32 vcc, v31, v56
	v_addc_co_u32_e32 v58, vcc, 0, v58, vcc
	v_cmp_eq_u32_e32 vcc, v30, v56
	v_addc_co_u32_e32 v58, vcc, 0, v58, vcc
	s_nop 0
	v_add_u32_dpp v57, v57, v57 row_shr:8 row_mask:0xf bank_mask:0xf bound_ctrl:1
	s_nop 1
	v_add_u32_dpp v57, v57, v57 row_bcast:15 row_mask:0xa bank_mask:0xf
	s_nop 1
	v_add_u32_dpp v57, v57, v57 row_bcast:31 row_mask:0xc bank_mask:0xf
	s_nop 0
	v_readlane_b32 s0, v57, 63
	v_add_u32_dpp v57, v58, v58 row_shr:1 row_mask:0xf bank_mask:0xf bound_ctrl:1
	s_sub_i32 s46, 0x100, s0
	s_nop 0
	v_add_u32_dpp v57, v57, v57 row_shr:2 row_mask:0xf bank_mask:0xf bound_ctrl:1
	s_nop 1
	v_add_u32_dpp v57, v57, v57 row_shr:4 row_mask:0xf bank_mask:0xf bound_ctrl:1
	s_nop 1
	v_add_u32_dpp v57, v57, v57 row_shr:8 row_mask:0xf bank_mask:0xf bound_ctrl:1
	s_nop 1
	v_add_u32_dpp v57, v57, v57 row_bcast:15 row_mask:0xa bank_mask:0xf
	s_nop 1
	v_add_u32_dpp v57, v57, v57 row_bcast:31 row_mask:0xc bank_mask:0xf
	s_nop 0
	v_readlane_b32 s1, v57, 63
	s_cmp_le_i32 s1, s46
	s_cbranch_scc1 .LBB0_454
	v_cmp_eq_u32_e64 s[4:5], v1, v56
	v_cmp_eq_u32_e64 s[76:77], v0, v56
	v_cmp_eq_u32_e64 s[78:79], v3, v56
	v_cmp_eq_u32_e64 s[80:81], v2, v56
	v_cmp_eq_u32_e64 s[82:83], v5, v56
	v_cmp_eq_u32_e64 s[84:85], v4, v56
	v_cmp_eq_u32_e64 s[86:87], v7, v56
	v_cmp_eq_u32_e64 s[88:89], v6, v56
	v_cmp_eq_u32_e64 s[90:91], v9, v56
	v_cmp_eq_u32_e64 s[92:93], v8, v56
	v_cmp_eq_u32_e64 s[94:95], v11, v56
	v_cmp_eq_u32_e64 s[96:97], v10, v56
	v_cmp_eq_u32_e64 s[6:7], v13, v56
	v_cmp_eq_u32_e64 s[10:11], v12, v56
	v_cmp_eq_u32_e64 s[0:1], v15, v56
	v_cmp_eq_u32_e64 s[12:13], v14, v56
	v_cmp_eq_u32_e64 s[14:15], v17, v56
	v_cmp_eq_u32_e64 s[16:17], v16, v56
	v_cmp_eq_u32_e64 s[18:19], v19, v56
	v_cmp_eq_u32_e64 s[20:21], v18, v56
	v_cmp_eq_u32_e64 s[22:23], v21, v56
	v_cmp_eq_u32_e64 s[74:75], v20, v56
	v_cmp_eq_u32_e64 s[24:25], v23, v56
	v_cmp_eq_u32_e64 s[26:27], v22, v56
	v_cmp_eq_u32_e64 s[28:29], v25, v56
	v_cmp_eq_u32_e64 s[30:31], v24, v56
	v_cmp_eq_u32_e64 s[34:35], v27, v56
	v_cmp_eq_u32_e64 s[36:37], v26, v56
	v_cmp_eq_u32_e64 s[38:39], v29, v56
	v_cmp_eq_u32_e64 s[40:41], v28, v56
	v_cmp_eq_u32_e64 s[42:43], v31, v56
	v_cmp_eq_u32_e64 s[44:45], v30, v56
	s_mov_b32 s47, 0
	s_mov_b32 s64, 10

;     ...
;         const unsigned cand = T | (1u << bit);
;         unsigned c0 = 0u;
; #pragma unroll
;         for (int j = 0; j < NJ; ++j) asm("v_cmp_ge_u32_e32 vcc, %1, %2\n\tv_addc_co_u32_e32 %0, vcc, 0, %0, vcc" : "+v"(c0) : "v"(key[j]), "v"(cand) : "vcc");
;         const int cnt = wave_count6(c0);
;         if (cnt >= 256) T = cand;
;         if (cnt == 256) break;
;     }
.LBB0_459:
	v_lshlrev_b32_e64 v26, v25, 1
	v_mov_b32_e32 v27, 0
	v_or_b32_e32 v26, v26, v24
	v_cmp_ge_u32_e32 vcc, v1, v26
	v_cmp_ge_u32_e64 s[100:101], v0, v26
	v_cmp_ge_u32_e64 s[0:1], v3, v26
	v_addc_co_u32_e32 v27, vcc, 0, v27, vcc
	v_addc_co_u32_e64 v27, s[100:101], 0, v27, s[100:101]
	v_addc_co_u32_e64 v27, s[0:1], 0, v27, s[0:1]
	v_cmp_ge_u32_e32 vcc, v2, v26
	v_cmp_ge_u32_e64 s[100:101], v5, v26
	v_cmp_ge_u32_e64 s[0:1], v4, v26
	v_addc_co_u32_e32 v27, vcc, 0, v27, vcc
	v_addc_co_u32_e64 v27, s[100:101], 0, v27, s[100:101]
	v_addc_co_u32_e64 v27, s[0:1], 0, v27, s[0:1]
	v_cmp_ge_u32_e32 vcc, v7, v26
	v_cmp_ge_u32_e64 s[100:101], v6, v26
	v_cmp_ge_u32_e64 s[0:1], v9, v26
	v_addc_co_u32_e32 v27, vcc, 0, v27, vcc
	v_addc_co_u32_e64 v27, s[100:101], 0, v27, s[100:101]
	v_addc_co_u32_e64 v27, s[0:1], 0, v27, s[0:1]
	v_cmp_ge_u32_e32 vcc, v8, v26
	v_cmp_ge_u32_e64 s[100:101], v11, v26
	v_cmp_ge_u32_e64 s[0:1], v10, v26
	v_addc_co_u32_e32 v27, vcc, 0, v27, vcc
	v_addc_co_u32_e64 v27, s[100:101], 0, v27, s[100:101]
	v_addc_co_u32_e64 v27, s[0:1], 0, v27, s[0:1]
	v_cmp_ge_u32_e32 vcc, v13, v26
	v_cmp_ge_u32_e64 s[100:101], v12, v26
	v_cmp_ge_u32_e64 s[0:1], v15, v26
	v_addc_co_u32_e32 v27, vcc, 0, v27, vcc
	v_addc_co_u32_e64 v27, s[100:101], 0, v27, s[100:101]
	v_addc_co_u32_e64 v27, s[0:1], 0, v27, s[0:1]
	v_cmp_ge_u32_e32 vcc, v14, v26
	v_cmp_ge_u32_e64 s[100:101], v17, v26
	v_cmp_ge_u32_e64 s[0:1], v16, v26
	v_addc_co_u32_e32 v27, vcc, 0, v27, vcc
	v_addc_co_u32_e64 v27, s[100:101], 0, v27, s[100:101]
	v_addc_co_u32_e64 v27, s[0:1], 0, v27, s[0:1]
	v_cmp_ge_u32_e32 vcc, v19, v26
	v_cmp_ge_u32_e64 s[100:101], v18, v26
	v_cmp_ge_u32_e64 s[0:1], v21, v26
	v_addc_co_u32_e32 v27, vcc, 0, v27, vcc
	v_addc_co_u32_e64 v27, s[100:101], 0, v27, s[100:101]
	v_addc_co_u32_e64 v27, s[0:1], 0, v27, s[0:1]
	v_cmp_ge_u32_e32 vcc, v20, v26
	v_cmp_ge_u32_e64 s[100:101], v23, v26
	v_cmp_ge_u32_e64 s[0:1], v22, v26
	v_addc_co_u32_e32 v27, vcc, 0, v27, vcc
	v_addc_co_u32_e64 v27, s[100:101], 0, v27, s[100:101]
	v_addc_co_u32_e64 v27, s[0:1], 0, v27, s[0:1]
	s_nop 1
	v_add_u32_dpp v27, v27, v27 row_shr:1 row_mask:0xf bank_mask:0xf bound_ctrl:1
	s_nop 1
	v_add_u32_dpp v27, v27, v27 row_shr:2 row_mask:0xf bank_mask:0xf bound_ctrl:1
	s_nop 1
	v_add_u32_dpp v27, v27, v27 row_shr:4 row_mask:0xf bank_mask:0xf bound_ctrl:1
	s_nop 1
	v_add_u32_dpp v27, v27, v27 row_shr:8 row_mask:0xf bank_mask:0xf bound_ctrl:1
	s_nop 1
	v_add_u32_dpp v27, v27, v27 row_bcast:15 row_mask:0xa bank_mask:0xf
	s_nop 1
	v_add_u32_dpp v27, v27, v27 row_bcast:31 row_mask:0xc bank_mask:0xf
	s_nop 0
	v_readlane_b32 s0, v27, 63
	s_cmpk_gt_i32 s0, 0xff
	s_cselect_b64 vcc, -1, 0
	s_cmpk_eq_i32 s0, 0x100
	v_cndmask_b32_e32 v24, v24, v26, vcc
	s_cselect_b64 s[0:1], -1, 0
	v_subrev_co_u32_e32 v25, vcc, 1, v25
	s_or_b64 s[0:1], s[0:1], vcc
	s_andn2_b64 vcc, exec, s[0:1]
	s_cbranch_vccnz .LBB0_459
;     ...
;     unsigned cg = 0u, ce = 0u;
; #pragma unroll
;     for (int j = 0; j < NJ; ++j) { asm("v_cmp_gt_u32_e32 vcc, %1, %2\n\tv_addc_co_u32_e32 %0, vcc, 0, %0, vcc" : "+v"(cg) : "v"(key[j]), "v"(T) : "vcc");
;                                    asm("v_cmp_eq_u32_e32 vcc, %1, %2\n\tv_addc_co_u32_e32 %0, vcc, 0, %0, vcc" : "+v"(ce) : "v"(key[j]), "v"(T) : "vcc"); }
;     const int gt = wave_count6(cg), eq = wave_count6(ce);
;     const int need = 256 - gt; int lim = SEQ;
;     if (eq > need) {
;         int X = 0;
; #pragma unroll 1
;     ...
; #pragma unroll
;             for (int j = 0; j < NJ; ++j) f += (key[j] == T && lane < c - 64 * j) ? 1u : 0u;
	v_mov_b32_e32 v25, v98
	v_cmp_gt_u32_e32 vcc, v1, v24
	v_addc_co_u32_e32 v25, vcc, 0, v25, vcc
	v_mov_b32_e32 v26, v98
	v_cmp_gt_u32_e32 vcc, v0, v24
	v_addc_co_u32_e32 v25, vcc, 0, v25, vcc
	s_movk_i32 s45, 0x800
	v_cmp_gt_u32_e32 vcc, v3, v24
	v_addc_co_u32_e32 v25, vcc, 0, v25, vcc
	v_cmp_gt_u32_e32 vcc, v2, v24
	v_addc_co_u32_e32 v25, vcc, 0, v25, vcc
	v_cmp_gt_u32_e32 vcc, v5, v24
	v_addc_co_u32_e32 v25, vcc, 0, v25, vcc
	v_cmp_gt_u32_e32 vcc, v4, v24
	v_addc_co_u32_e32 v25, vcc, 0, v25, vcc
	v_cmp_gt_u32_e32 vcc, v7, v24
	v_addc_co_u32_e32 v25, vcc, 0, v25, vcc
	v_cmp_eq_u32_e32 vcc, v1, v24
	v_addc_co_u32_e32 v26, vcc, 0, v26, vcc
	v_cmp_gt_u32_e32 vcc, v6, v24
	v_addc_co_u32_e32 v25, vcc, 0, v25, vcc
	v_cmp_eq_u32_e32 vcc, v0, v24
	v_addc_co_u32_e32 v26, vcc, 0, v26, vcc
	v_cmp_gt_u32_e32 vcc, v9, v24
	v_addc_co_u32_e32 v25, vcc, 0, v25, vcc
	v_cmp_eq_u32_e32 vcc, v3, v24
	v_addc_co_u32_e32 v26, vcc, 0, v26, vcc
	v_cmp_gt_u32_e32 vcc, v8, v24
	v_addc_co_u32_e32 v25, vcc, 0, v25, vcc
	v_cmp_eq_u32_e32 vcc, v2, v24
	v_addc_co_u32_e32 v26, vcc, 0, v26, vcc
	v_cmp_gt_u32_e32 vcc, v11, v24
	v_addc_co_u32_e32 v25, vcc, 0, v25, vcc
	v_cmp_eq_u32_e32 vcc, v5, v24
	v_addc_co_u32_e32 v26, vcc, 0, v26, vcc
	v_cmp_gt_u32_e32 vcc, v10, v24
	v_addc_co_u32_e32 v25, vcc, 0, v25, vcc
	v_cmp_eq_u32_e32 vcc, v4, v24
	v_addc_co_u32_e32 v26, vcc, 0, v26, vcc
	v_cmp_gt_u32_e32 vcc, v13, v24
	v_addc_co_u32_e32 v25, vcc, 0, v25, vcc
	v_cmp_eq_u32_e32 vcc, v7, v24
	v_addc_co_u32_e32 v26, vcc, 0, v26, vcc
	v_cmp_gt_u32_e32 vcc, v12, v24
	v_addc_co_u32_e32 v25, vcc, 0, v25, vcc
	v_cmp_eq_u32_e32 vcc, v6, v24
	v_addc_co_u32_e32 v26, vcc, 0, v26, vcc
	v_cmp_gt_u32_e32 vcc, v15, v24
	v_addc_co_u32_e32 v25, vcc, 0, v25, vcc
	v_cmp_eq_u32_e32 vcc, v9, v24
	v_addc_co_u32_e32 v26, vcc, 0, v26, vcc
	v_cmp_gt_u32_e32 vcc, v14, v24
	v_addc_co_u32_e32 v25, vcc, 0, v25, vcc
	v_cmp_eq_u32_e32 vcc, v8, v24
	v_addc_co_u32_e32 v26, vcc, 0, v26, vcc
	v_cmp_gt_u32_e32 vcc, v17, v24
	v_addc_co_u32_e32 v25, vcc, 0, v25, vcc
	v_cmp_eq_u32_e32 vcc, v11, v24
	v_addc_co_u32_e32 v26, vcc, 0, v26, vcc
	v_cmp_gt_u32_e32 vcc, v16, v24
	v_addc_co_u32_e32 v25, vcc, 0, v25, vcc
	v_cmp_eq_u32_e32 vcc, v10, v24
	v_addc_co_u32_e32 v26, vcc, 0, v26, vcc
	v_cmp_gt_u32_e32 vcc, v19, v24
	v_addc_co_u32_e32 v25, vcc, 0, v25, vcc
	v_cmp_eq_u32_e32 vcc, v13, v24
	v_addc_co_u32_e32 v26, vcc, 0, v26, vcc
	v_cmp_gt_u32_e32 vcc, v18, v24
	v_addc_co_u32_e32 v25, vcc, 0, v25, vcc
	v_cmp_eq_u32_e32 vcc, v12, v24
	v_addc_co_u32_e32 v26, vcc, 0, v26, vcc
	v_cmp_gt_u32_e32 vcc, v21, v24
	v_addc_co_u32_e32 v25, vcc, 0, v25, vcc
	v_cmp_eq_u32_e32 vcc, v15, v24
	v_addc_co_u32_e32 v26, vcc, 0, v26, vcc
	v_cmp_gt_u32_e32 vcc, v20, v24
	v_addc_co_u32_e32 v25, vcc, 0, v25, vcc
	v_cmp_eq_u32_e32 vcc, v14, v24
	v_addc_co_u32_e32 v26, vcc, 0, v26, vcc
	v_cmp_gt_u32_e32 vcc, v23, v24
	v_addc_co_u32_e32 v25, vcc, 0, v25, vcc
	v_cmp_eq_u32_e32 vcc, v17, v24
	v_addc_co_u32_e32 v26, vcc, 0, v26, vcc
	v_cmp_gt_u32_e32 vcc, v22, v24
	v_addc_co_u32_e32 v25, vcc, 0, v25, vcc
	v_cmp_eq_u32_e32 vcc, v16, v24
	v_addc_co_u32_e32 v26, vcc, 0, v26, vcc
	s_nop 0
	v_add_u32_dpp v25, v25, v25 row_shr:1 row_mask:0xf bank_mask:0xf bound_ctrl:1
	v_cmp_eq_u32_e32 vcc, v19, v24
	v_addc_co_u32_e32 v26, vcc, 0, v26, vcc
	v_cmp_eq_u32_e32 vcc, v18, v24
	v_addc_co_u32_e32 v26, vcc, 0, v26, vcc
	s_nop 0
	v_add_u32_dpp v25, v25, v25 row_shr:2 row_mask:0xf bank_mask:0xf bound_ctrl:1
	v_cmp_eq_u32_e32 vcc, v21, v24
	v_addc_co_u32_e32 v26, vcc, 0, v26, vcc
	v_cmp_eq_u32_e32 vcc, v20, v24
	v_addc_co_u32_e32 v26, vcc, 0, v26, vcc
	s_nop 0
	v_add_u32_dpp v25, v25, v25 row_shr:4 row_mask:0xf bank_mask:0xf bound_ctrl:1
	v_cmp_eq_u32_e32 vcc, v23, v24
	v_addc_co_u32_e32 v26, vcc, 0, v26, vcc
	v_cmp_eq_u32_e32 vcc, v22, v24
	v_addc_co_u32_e32 v26, vcc, 0, v26, vcc
	s_nop 0
	v_add_u32_dpp v25, v25, v25 row_shr:8 row_mask:0xf bank_mask:0xf bound_ctrl:1
	s_nop 1
	v_add_u32_dpp v25, v25, v25 row_bcast:15 row_mask:0xa bank_mask:0xf
	s_nop 1
	v_add_u32_dpp v25, v25, v25 row_bcast:31 row_mask:0xc bank_mask:0xf
	s_nop 0
	v_readlane_b32 s0, v25, 63
	v_add_u32_dpp v25, v26, v26 row_shr:1 row_mask:0xf bank_mask:0xf bound_ctrl:1
	s_sub_i32 s44, 0x100, s0
	s_nop 0
	v_add_u32_dpp v25, v25, v25 row_shr:2 row_mask:0xf bank_mask:0xf bound_ctrl:1
	s_nop 1
	v_add_u32_dpp v25, v25, v25 row_shr:4 row_mask:0xf bank_mask:0xf bound_ctrl:1
	s_nop 1
	v_add_u32_dpp v25, v25, v25 row_shr:8 row_mask:0xf bank_mask:0xf bound_ctrl:1
	s_nop 1
	v_add_u32_dpp v25, v25, v25 row_bcast:15 row_mask:0xa bank_mask:0xf
	s_nop 1
	v_add_u32_dpp v25, v25, v25 row_bcast:31 row_mask:0xc bank_mask:0xf
	s_nop 0
	v_readlane_b32 s1, v25, 63
	s_cmp_le_i32 s1, s44
	s_cbranch_scc1 .LBB0_464
	v_cmp_eq_u32_e32 vcc, v1, v24
	v_cmp_eq_u32_e64 s[0:1], v0, v24
	v_cmp_eq_u32_e64 s[4:5], v3, v24
	v_cmp_eq_u32_e64 s[6:7], v2, v24
	v_cmp_eq_u32_e64 s[10:11], v5, v24
	v_cmp_eq_u32_e64 s[12:13], v4, v24
	v_cmp_eq_u32_e64 s[14:15], v7, v24
	v_cmp_eq_u32_e64 s[16:17], v6, v24
	v_cmp_eq_u32_e64 s[18:19], v9, v24
	v_cmp_eq_u32_e64 s[20:21], v8, v24
	v_cmp_eq_u32_e64 s[22:23], v11, v24
	v_cmp_eq_u32_e64 s[24:25], v10, v24
	v_cmp_eq_u32_e64 s[26:27], v13, v24
	v_cmp_eq_u32_e64 s[28:29], v12, v24
	v_cmp_eq_u32_e64 s[30:31], v15, v24
	v_cmp_eq_u32_e64 s[34:35], v14, v24
	v_cmp_eq_u32_e64 s[36:37], v17, v24
	v_cmp_eq_u32_e64 s[38:39], v16, v24
	v_cmp_eq_u32_e64 s[40:41], v19, v24
	v_cmp_eq_u32_e64 s[42:43], v18, v24
	v_cmp_eq_u32_e64 s[74:75], v21, v24
	v_cmp_eq_u32_e64 s[76:77], v20, v24
	v_cmp_eq_u32_e64 s[78:79], v23, v24
	v_cmp_eq_u32_e64 s[80:81], v22, v24
	s_mov_b32 s45, 0
	s_mov_b32 s46, 10

;     ...
;         const unsigned cand = T | (1u << bit);
;         unsigned c0 = 0u;
; #pragma unroll
;         for (int j = 0; j < NJ; ++j) asm("v_cmp_ge_u32_e32 vcc, %1, %2\n\tv_addc_co_u32_e32 %0, vcc, 0, %0, vcc" : "+v"(c0) : "v"(key[j]), "v"(cand) : "vcc");
;         const int cnt = wave_count6(c0);
;         if (cnt >= 256) T = cand;
;         if (cnt == 256) break;
;     }
;     unsigned cg = 0u, ce = 0u;
; #pragma unroll
;     for (int j = 0; j < NJ; ++j) { asm("v_cmp_gt_u32_e32 vcc, %1, %2\n\tv_addc_co_u32_e32 %0, vcc, 0, %0, vcc" : "+v"(cg) : "v"(key[j]), "v"(T) : "vcc");
;                                    asm("v_cmp_eq_u32_e32 vcc, %1, %2\n\tv_addc_co_u32_e32 %0, vcc, 0, %0, vcc" : "+v"(ce) : "v"(key[j]), "v"(T) : "vcc"); }
;     const int gt = wave_count6(cg), eq = wave_count6(ce);
;     const int need = 256 - gt; int lim = SEQ;
;     if (eq > need) {
;         int X = 0;
; #pragma unroll 1
;     ...
; #pragma unroll
;             for (int j = 0; j < NJ; ++j) f += (key[j] == T && lane < c - 64 * j) ? 1u : 0u;
.LBB0_470:
	v_lshlrev_b32_e64 v18, v17, 1
	v_mov_b32_e32 v19, 0
	v_or_b32_e32 v18, v18, v16
	v_cmp_ge_u32_e32 vcc, v1, v18
	v_cmp_ge_u32_e64 s[100:101], v0, v18
	v_cmp_ge_u32_e64 s[0:1], v3, v18
	v_addc_co_u32_e32 v19, vcc, 0, v19, vcc
	v_addc_co_u32_e64 v19, s[100:101], 0, v19, s[100:101]
	v_addc_co_u32_e64 v19, s[0:1], 0, v19, s[0:1]
	v_cmp_ge_u32_e32 vcc, v2, v18
	v_cmp_ge_u32_e64 s[100:101], v5, v18
	v_cmp_ge_u32_e64 s[0:1], v4, v18
	v_addc_co_u32_e32 v19, vcc, 0, v19, vcc
	v_addc_co_u32_e64 v19, s[100:101], 0, v19, s[100:101]
	v_addc_co_u32_e64 v19, s[0:1], 0, v19, s[0:1]
	v_cmp_ge_u32_e32 vcc, v7, v18
	v_cmp_ge_u32_e64 s[100:101], v6, v18
	v_cmp_ge_u32_e64 s[0:1], v9, v18
	v_addc_co_u32_e32 v19, vcc, 0, v19, vcc
	v_addc_co_u32_e64 v19, s[100:101], 0, v19, s[100:101]
	v_addc_co_u32_e64 v19, s[0:1], 0, v19, s[0:1]
	v_cmp_ge_u32_e32 vcc, v8, v18
	v_cmp_ge_u32_e64 s[100:101], v11, v18
	v_cmp_ge_u32_e64 s[0:1], v10, v18
	v_addc_co_u32_e32 v19, vcc, 0, v19, vcc
	v_addc_co_u32_e64 v19, s[100:101], 0, v19, s[100:101]
	v_addc_co_u32_e64 v19, s[0:1], 0, v19, s[0:1]
	v_cmp_ge_u32_e32 vcc, v13, v18
	v_cmp_ge_u32_e64 s[100:101], v12, v18
	v_cmp_ge_u32_e64 s[0:1], v15, v18
	v_addc_co_u32_e32 v19, vcc, 0, v19, vcc
	v_addc_co_u32_e64 v19, s[100:101], 0, v19, s[100:101]
	v_addc_co_u32_e64 v19, s[0:1], 0, v19, s[0:1]
	v_cmp_ge_u32_e32 vcc, v14, v18
	v_addc_co_u32_e32 v19, vcc, 0, v19, vcc
	s_nop 1
	v_add_u32_dpp v19, v19, v19 row_shr:1 row_mask:0xf bank_mask:0xf bound_ctrl:1
	s_nop 1
	v_add_u32_dpp v19, v19, v19 row_shr:2 row_mask:0xf bank_mask:0xf bound_ctrl:1
	s_nop 1
	v_add_u32_dpp v19, v19, v19 row_shr:4 row_mask:0xf bank_mask:0xf bound_ctrl:1
	s_nop 1
	v_add_u32_dpp v19, v19, v19 row_shr:8 row_mask:0xf bank_mask:0xf bound_ctrl:1
	s_nop 1
	v_add_u32_dpp v19, v19, v19 row_bcast:15 row_mask:0xa bank_mask:0xf
	s_nop 1
	v_add_u32_dpp v19, v19, v19 row_bcast:31 row_mask:0xc bank_mask:0xf
	s_nop 0
	v_readlane_b32 s0, v19, 63
	s_cmpk_gt_i32 s0, 0xff
	s_cselect_b64 vcc, -1, 0
	s_cmpk_eq_i32 s0, 0x100
	v_cndmask_b32_e32 v16, v16, v18, vcc
	s_cselect_b64 s[0:1], -1, 0
	v_subrev_co_u32_e32 v17, vcc, 1, v17
	s_or_b64 s[0:1], s[0:1], vcc
	s_andn2_b64 vcc, exec, s[0:1]
	s_cbranch_vccnz .LBB0_470
	v_mov_b32_e32 v17, v98
	v_cmp_gt_u32_e32 vcc, v1, v16
	v_addc_co_u32_e32 v17, vcc, 0, v17, vcc
	v_mov_b32_e32 v18, v98
	v_cmp_gt_u32_e32 vcc, v0, v16
	v_addc_co_u32_e32 v17, vcc, 0, v17, vcc
	s_movk_i32 s40, 0x800
	v_cmp_gt_u32_e32 vcc, v3, v16
	v_addc_co_u32_e32 v17, vcc, 0, v17, vcc
	v_cmp_gt_u32_e32 vcc, v2, v16
	v_addc_co_u32_e32 v17, vcc, 0, v17, vcc
	v_cmp_gt_u32_e32 vcc, v5, v16
	v_addc_co_u32_e32 v17, vcc, 0, v17, vcc
	v_cmp_gt_u32_e32 vcc, v4, v16
	v_addc_co_u32_e32 v17, vcc, 0, v17, vcc
	v_cmp_gt_u32_e32 vcc, v7, v16
	v_addc_co_u32_e32 v17, vcc, 0, v17, vcc
	v_cmp_eq_u32_e32 vcc, v1, v16
	v_addc_co_u32_e32 v18, vcc, 0, v18, vcc
	v_cmp_gt_u32_e32 vcc, v6, v16
	v_addc_co_u32_e32 v17, vcc, 0, v17, vcc
	v_cmp_eq_u32_e32 vcc, v0, v16
	v_addc_co_u32_e32 v18, vcc, 0, v18, vcc
	v_cmp_gt_u32_e32 vcc, v9, v16
	v_addc_co_u32_e32 v17, vcc, 0, v17, vcc
	v_cmp_eq_u32_e32 vcc, v3, v16
	v_addc_co_u32_e32 v18, vcc, 0, v18, vcc
	v_cmp_gt_u32_e32 vcc, v8, v16
	v_addc_co_u32_e32 v17, vcc, 0, v17, vcc
	v_cmp_eq_u32_e32 vcc, v2, v16
	v_addc_co_u32_e32 v18, vcc, 0, v18, vcc
	v_cmp_gt_u32_e32 vcc, v11, v16
	v_addc_co_u32_e32 v17, vcc, 0, v17, vcc
	v_cmp_eq_u32_e32 vcc, v5, v16
	v_addc_co_u32_e32 v18, vcc, 0, v18, vcc
	v_cmp_gt_u32_e32 vcc, v10, v16
	v_addc_co_u32_e32 v17, vcc, 0, v17, vcc
	v_cmp_eq_u32_e32 vcc, v4, v16
	v_addc_co_u32_e32 v18, vcc, 0, v18, vcc
	v_cmp_gt_u32_e32 vcc, v13, v16
	v_addc_co_u32_e32 v17, vcc, 0, v17, vcc
	v_cmp_eq_u32_e32 vcc, v7, v16
	v_addc_co_u32_e32 v18, vcc, 0, v18, vcc
	v_cmp_gt_u32_e32 vcc, v12, v16
	v_addc_co_u32_e32 v17, vcc, 0, v17, vcc
	v_cmp_eq_u32_e32 vcc, v6, v16
	v_addc_co_u32_e32 v18, vcc, 0, v18, vcc
	v_cmp_gt_u32_e32 vcc, v15, v16
	v_addc_co_u32_e32 v17, vcc, 0, v17, vcc
	v_cmp_eq_u32_e32 vcc, v9, v16
	v_addc_co_u32_e32 v18, vcc, 0, v18, vcc
	v_cmp_gt_u32_e32 vcc, v14, v16
	v_addc_co_u32_e32 v17, vcc, 0, v17, vcc
	v_cmp_eq_u32_e32 vcc, v8, v16
	v_addc_co_u32_e32 v18, vcc, 0, v18, vcc
	s_nop 0
	v_add_u32_dpp v17, v17, v17 row_shr:1 row_mask:0xf bank_mask:0xf bound_ctrl:1
	v_cmp_eq_u32_e32 vcc, v11, v16
	v_addc_co_u32_e32 v18, vcc, 0, v18, vcc
	v_cmp_eq_u32_e32 vcc, v10, v16
	v_addc_co_u32_e32 v18, vcc, 0, v18, vcc
	s_nop 0
	v_add_u32_dpp v17, v17, v17 row_shr:2 row_mask:0xf bank_mask:0xf bound_ctrl:1
	v_cmp_eq_u32_e32 vcc, v13, v16
	v_addc_co_u32_e32 v18, vcc, 0, v18, vcc
	v_cmp_eq_u32_e32 vcc, v12, v16
	v_addc_co_u32_e32 v18, vcc, 0, v18, vcc
	s_nop 0
	v_add_u32_dpp v17, v17, v17 row_shr:4 row_mask:0xf bank_mask:0xf bound_ctrl:1
	v_cmp_eq_u32_e32 vcc, v15, v16
	v_addc_co_u32_e32 v18, vcc, 0, v18, vcc
	v_cmp_eq_u32_e32 vcc, v14, v16
	v_addc_co_u32_e32 v18, vcc, 0, v18, vcc
	s_nop 0
	v_add_u32_dpp v17, v17, v17 row_shr:8 row_mask:0xf bank_mask:0xf bound_ctrl:1
	s_nop 1
	v_add_u32_dpp v17, v17, v17 row_bcast:15 row_mask:0xa bank_mask:0xf
	s_nop 1
	v_add_u32_dpp v17, v17, v17 row_bcast:31 row_mask:0xc bank_mask:0xf
	s_nop 0
	v_readlane_b32 s0, v17, 63
	v_add_u32_dpp v17, v18, v18 row_shr:1 row_mask:0xf bank_mask:0xf bound_ctrl:1
	s_sub_i32 s38, 0x100, s0
	s_nop 0
	v_add_u32_dpp v17, v17, v17 row_shr:2 row_mask:0xf bank_mask:0xf bound_ctrl:1
	s_nop 1
	v_add_u32_dpp v17, v17, v17 row_shr:4 row_mask:0xf bank_mask:0xf bound_ctrl:1
	s_nop 1
	v_add_u32_dpp v17, v17, v17 row_shr:8 row_mask:0xf bank_mask:0xf bound_ctrl:1
	s_nop 1
	v_add_u32_dpp v17, v17, v17 row_bcast:15 row_mask:0xa bank_mask:0xf
	s_nop 1
	v_add_u32_dpp v17, v17, v17 row_bcast:31 row_mask:0xc bank_mask:0xf
	s_nop 0
	v_readlane_b32 s1, v17, 63
	s_cmp_le_i32 s1, s38
	s_cbranch_scc1 .LBB0_475
	v_cmp_eq_u32_e32 vcc, v1, v16
	v_cmp_eq_u32_e64 s[0:1], v0, v16
	v_cmp_eq_u32_e64 s[4:5], v3, v16
	v_cmp_eq_u32_e64 s[6:7], v2, v16
	v_cmp_eq_u32_e64 s[10:11], v5, v16
	v_cmp_eq_u32_e64 s[12:13], v4, v16
	v_cmp_eq_u32_e64 s[14:15], v7, v16
	v_cmp_eq_u32_e64 s[16:17], v6, v16
	v_cmp_eq_u32_e64 s[18:19], v9, v16
	v_cmp_eq_u32_e64 s[20:21], v8, v16
	v_cmp_eq_u32_e64 s[22:23], v11, v16
	v_cmp_eq_u32_e64 s[24:25], v10, v16
	v_cmp_eq_u32_e64 s[26:27], v13, v16
	v_cmp_eq_u32_e64 s[28:29], v12, v16
	v_cmp_eq_u32_e64 s[30:31], v15, v16
	v_cmp_eq_u32_e64 s[34:35], v14, v16
	s_mov_b32 s39, 0
	s_mov_b32 s40, 10

;     ...
;         const unsigned cand = T | (1u << bit);
;         unsigned c0 = 0u;
; #pragma unroll
;         for (int j = 0; j < NJ; ++j) asm("v_cmp_ge_u32_e32 vcc, %1, %2\n\tv_addc_co_u32_e32 %0, vcc, 0, %0, vcc" : "+v"(c0) : "v"(key[j]), "v"(cand) : "vcc");
;         const int cnt = wave_count6(c0);
;         if (cnt >= 256) T = cand;
;         if (cnt == 256) break;
;     }
;     unsigned cg = 0u, ce = 0u;
; #pragma unroll
;     for (int j = 0; j < NJ; ++j) { asm("v_cmp_gt_u32_e32 vcc, %1, %2\n\tv_addc_co_u32_e32 %0, vcc, 0, %0, vcc" : "+v"(cg) : "v"(key[j]), "v"(T) : "vcc");
;                                    asm("v_cmp_eq_u32_e32 vcc, %1, %2\n\tv_addc_co_u32_e32 %0, vcc, 0, %0, vcc" : "+v"(ce) : "v"(key[j]), "v"(T) : "vcc"); }
;     const int gt = wave_count6(cg), eq = wave_count6(ce);
;     const int need = 256 - gt; int lim = SEQ;
;     if (eq > need) {
;         int X = 0;
; #pragma unroll 1
;     ...
; #pragma unroll
;             for (int j = 0; j < NJ; ++j) f += (key[j] == T && lane < c - 64 * j) ? 1u : 0u;
.LBB0_480:
	v_lshlrev_b32_e64 v10, v9, 1
	v_mov_b32_e32 v11, 0
	v_or_b32_e32 v10, v10, v8
	v_cmp_ge_u32_e32 vcc, v1, v10
	v_cmp_ge_u32_e64 s[100:101], v0, v10
	v_cmp_ge_u32_e64 s[0:1], v3, v10
	v_addc_co_u32_e32 v11, vcc, 0, v11, vcc
	v_addc_co_u32_e64 v11, s[100:101], 0, v11, s[100:101]
	v_addc_co_u32_e64 v11, s[0:1], 0, v11, s[0:1]
	v_cmp_ge_u32_e32 vcc, v2, v10
	v_cmp_ge_u32_e64 s[100:101], v5, v10
	v_cmp_ge_u32_e64 s[0:1], v4, v10
	v_addc_co_u32_e32 v11, vcc, 0, v11, vcc
	v_addc_co_u32_e64 v11, s[100:101], 0, v11, s[100:101]
	v_addc_co_u32_e64 v11, s[0:1], 0, v11, s[0:1]
	v_cmp_ge_u32_e32 vcc, v7, v10
	v_cmp_ge_u32_e64 s[100:101], v6, v10
	v_addc_co_u32_e32 v11, vcc, 0, v11, vcc
	v_addc_co_u32_e64 v11, s[100:101], 0, v11, s[100:101]
	s_nop 1
	v_add_u32_dpp v11, v11, v11 row_shr:1 row_mask:0xf bank_mask:0xf bound_ctrl:1
	s_nop 1
	v_add_u32_dpp v11, v11, v11 row_shr:2 row_mask:0xf bank_mask:0xf bound_ctrl:1
	s_nop 1
	v_add_u32_dpp v11, v11, v11 row_shr:4 row_mask:0xf bank_mask:0xf bound_ctrl:1
	s_nop 1
	v_add_u32_dpp v11, v11, v11 row_shr:8 row_mask:0xf bank_mask:0xf bound_ctrl:1
	s_nop 1
	v_add_u32_dpp v11, v11, v11 row_bcast:15 row_mask:0xa bank_mask:0xf
	s_nop 1
	v_add_u32_dpp v11, v11, v11 row_bcast:31 row_mask:0xc bank_mask:0xf
	s_nop 0
	v_readlane_b32 s0, v11, 63
	s_cmpk_gt_i32 s0, 0xff
	s_cselect_b64 vcc, -1, 0
	s_cmpk_eq_i32 s0, 0x100
	v_cndmask_b32_e32 v8, v8, v10, vcc
	s_cselect_b64 s[0:1], -1, 0
	v_subrev_co_u32_e32 v9, vcc, 1, v9
	s_or_b64 s[0:1], s[0:1], vcc
	s_andn2_b64 vcc, exec, s[0:1]
	s_cbranch_vccnz .LBB0_480
	v_mov_b32_e32 v9, v98
	v_cmp_gt_u32_e32 vcc, v1, v8
	v_addc_co_u32_e32 v9, vcc, 0, v9, vcc
	v_mov_b32_e32 v10, v98
	v_cmp_gt_u32_e32 vcc, v0, v8
	v_addc_co_u32_e32 v9, vcc, 0, v9, vcc
	s_movk_i32 s22, 0x800
	v_cmp_gt_u32_e32 vcc, v3, v8
	v_addc_co_u32_e32 v9, vcc, 0, v9, vcc
	v_cmp_gt_u32_e32 vcc, v2, v8
	v_addc_co_u32_e32 v9, vcc, 0, v9, vcc
	v_cmp_gt_u32_e32 vcc, v5, v8
	v_addc_co_u32_e32 v9, vcc, 0, v9, vcc
	v_cmp_gt_u32_e32 vcc, v4, v8
	v_addc_co_u32_e32 v9, vcc, 0, v9, vcc
	v_cmp_gt_u32_e32 vcc, v7, v8
	v_addc_co_u32_e32 v9, vcc, 0, v9, vcc
	v_cmp_eq_u32_e32 vcc, v1, v8
	v_addc_co_u32_e32 v10, vcc, 0, v10, vcc
	v_cmp_gt_u32_e32 vcc, v6, v8
	v_addc_co_u32_e32 v9, vcc, 0, v9, vcc
	v_cmp_eq_u32_e32 vcc, v0, v8
	v_addc_co_u32_e32 v10, vcc, 0, v10, vcc
	s_nop 0
	v_add_u32_dpp v9, v9, v9 row_shr:1 row_mask:0xf bank_mask:0xf bound_ctrl:1
	v_cmp_eq_u32_e32 vcc, v3, v8
	v_addc_co_u32_e32 v10, vcc, 0, v10, vcc
	v_cmp_eq_u32_e32 vcc, v2, v8
	v_addc_co_u32_e32 v10, vcc, 0, v10, vcc
	s_nop 0
	v_add_u32_dpp v9, v9, v9 row_shr:2 row_mask:0xf bank_mask:0xf bound_ctrl:1
	v_cmp_eq_u32_e32 vcc, v5, v8
	v_addc_co_u32_e32 v10, vcc, 0, v10, vcc
	v_cmp_eq_u32_e32 vcc, v4, v8
	v_addc_co_u32_e32 v10, vcc, 0, v10, vcc
	s_nop 0
	v_add_u32_dpp v9, v9, v9 row_shr:4 row_mask:0xf bank_mask:0xf bound_ctrl:1
	v_cmp_eq_u32_e32 vcc, v7, v8
	v_addc_co_u32_e32 v10, vcc, 0, v10, vcc
	v_cmp_eq_u32_e32 vcc, v6, v8
	v_addc_co_u32_e32 v10, vcc, 0, v10, vcc
	s_nop 0
	v_add_u32_dpp v9, v9, v9 row_shr:8 row_mask:0xf bank_mask:0xf bound_ctrl:1
	s_nop 1
	v_add_u32_dpp v9, v9, v9 row_bcast:15 row_mask:0xa bank_mask:0xf
	s_nop 1
	v_add_u32_dpp v9, v9, v9 row_bcast:31 row_mask:0xc bank_mask:0xf
	s_nop 0
	v_readlane_b32 s0, v9, 63
	v_add_u32_dpp v9, v10, v10 row_shr:1 row_mask:0xf bank_mask:0xf bound_ctrl:1
	s_sub_i32 s20, 0x100, s0
	s_nop 0
	v_add_u32_dpp v9, v9, v9 row_shr:2 row_mask:0xf bank_mask:0xf bound_ctrl:1
	s_nop 1
	v_add_u32_dpp v9, v9, v9 row_shr:4 row_mask:0xf bank_mask:0xf bound_ctrl:1
	s_nop 1
	v_add_u32_dpp v9, v9, v9 row_shr:8 row_mask:0xf bank_mask:0xf bound_ctrl:1
	s_nop 1
	v_add_u32_dpp v9, v9, v9 row_bcast:15 row_mask:0xa bank_mask:0xf
	s_nop 1
	v_add_u32_dpp v9, v9, v9 row_bcast:31 row_mask:0xc bank_mask:0xf
	s_nop 0
	v_readlane_b32 s1, v9, 63
	s_cmp_le_i32 s1, s20
	s_cbranch_scc1 .LBB0_485
	v_cmp_eq_u32_e32 vcc, v1, v8
	v_cmp_eq_u32_e64 s[0:1], v0, v8
	v_cmp_eq_u32_e64 s[4:5], v3, v8
	v_cmp_eq_u32_e64 s[6:7], v2, v8
	v_cmp_eq_u32_e64 s[10:11], v5, v8
	v_cmp_eq_u32_e64 s[12:13], v4, v8
	v_cmp_eq_u32_e64 s[14:15], v7, v8
	v_cmp_eq_u32_e64 s[16:17], v6, v8
	s_mov_b32 s21, 0
	s_mov_b32 s22, 10
